# row-wise phases: wave-wide sum of squares via v_permlane32/16_swap + DPP row rotations instead of six ds_bpermute LDS round trips (same butterfly order)
# speedup vs baseline: 1.0068x; 1.0068x over previous
.LBB0_14:
	v_add_u32_e32 v9, 0xffffc000, v0
	v_cmp_gt_i32_e32 vcc, s69, v0
	v_mov_b32_e32 v11, s49
	v_mov_b32_e32 v24, s45
	v_cndmask_b32_e32 v23, 0, v1, vcc
	v_mov_b32_e32 v26, s48
	v_mov_b32_e32 v27, s44
	v_min_i32_e32 v28, 0x4000, v0
	v_cndmask_b32_e32 v22, v9, v0, vcc
	v_cndmask_b32_e32 v25, v11, v24, vcc
	v_cndmask_b32_e32 v24, v26, v27, vcc
	v_ashrrev_i32_e32 v9, 13, v28
	v_lshlrev_b64 v[22:23], 12, v[22:23]
	v_mul_hi_i32_i24_e32 v27, 0x6000, v9
	v_mul_i32_i24_e32 v26, 0x6000, v9
	v_lshl_add_u64 v[22:23], v[24:25], 0, v[22:23]
	v_lshl_add_u64 v[24:25], s[12:13], 0, v[26:27]
	v_lshl_add_u64 v[34:35], v[22:23], 0, v[192:193]
	global_load_dwordx4 v[18:21], v[2:3], off
	v_lshl_add_u64 v[46:47], v[24:25], 0, s[34:35]
	v_lshl_add_u64 v[48:49], v[24:25], 0, v[192:193]
	global_load_dwordx4 v[22:25], v[34:35], off
	global_load_dwordx4 v[26:29], v[34:35], off offset:1024
	global_load_dwordx4 v[30:33], v[34:35], off offset:2048
	s_nop 0
	global_load_dwordx4 v[34:37], v[34:35], off offset:3072
	v_lshl_add_u64 v[38:39], v[46:47], 0, v[192:193]
	global_load_dwordx4 v[38:41], v[38:39], off
	s_nop 0
	global_load_dwordx4 v[42:45], v[48:49], off
	v_lshl_add_u64 v[96:97], v[46:47], 0, v[192:193]
	global_load_dwordx4 v[100:103], v[2:3], off offset:1024
	global_load_dwordx4 v[112:115], v[96:97], off offset:1024
	global_load_dwordx4 v[124:127], v[48:49], off offset:1024
	global_load_dwordx4 v[104:107], v[2:3], off offset:2048
	global_load_dwordx4 v[116:119], v[96:97], off offset:2048
	global_load_dwordx4 v[128:131], v[48:49], off offset:2048
	global_load_dwordx4 v[108:111], v[2:3], off offset:3072
	global_load_dwordx4 v[120:123], v[96:97], off offset:3072
	global_load_dwordx4 v[132:135], v[48:49], off offset:3072
	v_mov_b32_e32 v7, v193
	v_lshl_add_u64 v[50:51], v[46:47], 0, v[6:7]
	v_mov_b32_e32 v11, v193
	s_movk_i32 s2, 0x41ff
	v_lshl_add_u64 v[0:1], v[0:1], 0, s[38:39]
	v_cmp_lt_i32_e32 vcc, s2, v0
	s_or_b64 s[42:43], vcc, s[42:43]
	s_waitcnt vmcnt(14)
	v_mul_f32_e32 v7, v23, v23
	s_waitcnt vmcnt(13)
	v_mul_f32_e32 v9, v27, v27
	s_waitcnt vmcnt(12)
	v_mov_b32_e32 v54, v31
	s_waitcnt vmcnt(11)
	v_mov_b32_e32 v55, v35
	v_mov_b32_e32 v52, v30
	v_mov_b32_e32 v53, v34
	v_fmac_f32_e32 v7, v22, v22
	v_fmac_f32_e32 v9, v26, v26
	v_pk_mul_f32 v[54:55], v[54:55], v[54:55]
	v_mov_b32_e32 v56, v32
	v_mov_b32_e32 v57, v36
	v_fmac_f32_e32 v7, v24, v24
	v_fmac_f32_e32 v9, v28, v28
	v_pk_fma_f32 v[52:53], v[52:53], v[52:53], v[54:55]
	v_mov_b32_e32 v58, v33
	v_mov_b32_e32 v59, v37
	v_fmac_f32_e32 v7, v25, v25
	v_fmac_f32_e32 v9, v29, v29
	v_pk_fma_f32 v[52:53], v[56:57], v[56:57], v[52:53]
	v_add_f32_e32 v7, v7, v9
	v_pk_fma_f32 v[52:53], v[58:59], v[58:59], v[52:53]
	s_waitcnt vmcnt(10)
	v_pk_add_f32 v[38:39], v[38:39], 1.0 op_sel_hi:[1,0]
	v_add_f32_e32 v7, v7, v52
	v_add_f32_e32 v7, v7, v53
	v_pk_add_f32 v[40:41], v[40:41], 1.0 op_sel_hi:[1,0]
	s_waitcnt lgkmcnt(0)
	v_mov_b32_e32 v9, v7
	s_nop 1
	v_permlane32_swap_b32_e32 v9, v7
	v_add_f32_e32 v7, v7, v9
	v_mov_b32_e32 v9, v7
	s_nop 1
	v_permlane16_swap_b32_e32 v9, v7
	v_add_f32_e32 v7, v7, v9
	s_nop 1
	v_add_f32_dpp v7, v7, v7 row_ror:8 row_mask:0xf bank_mask:0xf
	s_nop 1
	v_add_f32_dpp v7, v7, v7 row_ror:4 row_mask:0xf bank_mask:0xf
	s_nop 1
	v_add_f32_dpp v7, v7, v7 row_ror:2 row_mask:0xf bank_mask:0xf
	s_nop 1
	v_add_f32_dpp v7, v7, v7 row_ror:1 row_mask:0xf bank_mask:0xf
	v_fmamk_f32 v7, v7, 0x3a800000, v221
	v_rsq_f32_e32 v52, v7
	v_mov_b32_e32 v9, v193
	v_pk_mul_f32 v[22:23], v[22:23], v[52:53] op_sel_hi:[1,0]
	v_pk_mul_f32 v[24:25], v[24:25], v[52:53] op_sel_hi:[1,0]
	v_pk_mul_f32 v[18:19], v[18:19], v[22:23]
	v_pk_mul_f32 v[20:21], v[20:21], v[24:25]
	s_waitcnt vmcnt(9)
	v_pk_fma_f32 v[18:19], v[38:39], v[18:19], v[42:43]
	v_pk_fma_f32 v[20:21], v[40:41], v[20:21], v[44:45]
	v_cvt_pk_bf16_f32 v18, v18, v19
	v_cvt_pk_bf16_f32 v19, v20, v21
	global_store_dwordx2 v[4:5], v[18:19], off
	s_nop 0
	s_nop 0
	s_nop 0
	s_nop 0
	v_pk_mul_f32 v[26:27], v[26:27], v[52:53] op_sel_hi:[1,0]
	v_pk_mul_f32 v[28:29], v[28:29], v[52:53] op_sel_hi:[1,0]
	v_lshl_add_u64 v[42:43], v[46:47], 0, v[8:9]
	v_pk_mul_f32 v[30:31], v[30:31], v[52:53] op_sel_hi:[1,0]
	v_pk_mul_f32 v[32:33], v[32:33], v[52:53] op_sel_hi:[1,0]
	s_waitcnt vmcnt(9)
	v_pk_mul_f32 v[18:19], v[100:101], v[26:27]
	s_waitcnt vmcnt(8)
	v_pk_add_f32 v[22:23], v[112:113], 1.0 op_sel_hi:[1,0]
	v_pk_mul_f32 v[20:21], v[102:103], v[28:29]
	v_pk_add_f32 v[24:25], v[114:115], 1.0 op_sel_hi:[1,0]
	s_waitcnt vmcnt(7)
	v_pk_fma_f32 v[18:19], v[22:23], v[18:19], v[124:125]
	v_pk_fma_f32 v[20:21], v[24:25], v[20:21], v[126:127]
	v_cvt_pk_bf16_f32 v18, v18, v19
	v_cvt_pk_bf16_f32 v19, v20, v21
	global_store_dwordx2 v[4:5], v[18:19], off offset:512
	s_nop 0
	s_nop 0
	s_nop 0
	s_nop 0
	v_lshl_add_u64 v[38:39], v[46:47], 0, v[10:11]
	s_waitcnt vmcnt(7)
	v_pk_mul_f32 v[18:19], v[30:31], v[104:105]
	s_waitcnt vmcnt(6)
	v_pk_add_f32 v[22:23], v[116:117], 1.0 op_sel_hi:[1,0]
	v_pk_mul_f32 v[20:21], v[32:33], v[106:107]
	v_pk_add_f32 v[24:25], v[118:119], 1.0 op_sel_hi:[1,0]
	s_waitcnt vmcnt(5)
	v_pk_fma_f32 v[18:19], v[18:19], v[22:23], v[128:129]
	v_pk_fma_f32 v[20:21], v[20:21], v[24:25], v[130:131]
	v_cvt_pk_bf16_f32 v18, v18, v19
	v_cvt_pk_bf16_f32 v19, v20, v21
	global_store_dwordx2 v[4:5], v[18:19], off offset:1024
	s_nop 0
	s_nop 0
	s_nop 0
	s_nop 0
	v_pk_mul_f32 v[30:31], v[34:35], v[52:53] op_sel_hi:[1,0]
	v_pk_mul_f32 v[32:33], v[36:37], v[52:53] op_sel_hi:[1,0]
	s_waitcnt vmcnt(5)
	v_pk_mul_f32 v[18:19], v[30:31], v[108:109]
	s_waitcnt vmcnt(4)
	v_pk_add_f32 v[22:23], v[120:121], 1.0 op_sel_hi:[1,0]
	v_pk_mul_f32 v[20:21], v[32:33], v[110:111]
	v_pk_add_f32 v[24:25], v[122:123], 1.0 op_sel_hi:[1,0]
	s_waitcnt vmcnt(3)
	v_pk_fma_f32 v[18:19], v[18:19], v[22:23], v[132:133]
	v_pk_fma_f32 v[20:21], v[20:21], v[24:25], v[134:135]
	v_cvt_pk_bf16_f32 v18, v18, v19
	v_cvt_pk_bf16_f32 v19, v20, v21
	global_store_dwordx2 v[4:5], v[18:19], off offset:1536
	v_lshl_add_u64 v[4:5], v[4:5], 0, s[40:41]
	s_andn2_b64 exec, exec, s[42:43]
	s_cbranch_execnz .LBB0_14

.LBB0_28:
	v_lshl_add_u64 v[0:1], v[32:33], 0, v[30:31]
	global_load_dwordx2 v[12:13], v[0:1], off
	global_load_dwordx2 v[14:15], v[0:1], off offset:1536
	global_load_dwordx2 v[36:37], v[0:1], off offset:512
	global_load_dwordx2 v[38:39], v[0:1], off offset:1024
	v_readlane_b32 s8, v254, 9
	v_readlane_b32 s48, v254, 38
	v_readlane_b32 s20, v254, 21
	v_readlane_b32 s21, v254, 22
	v_readlane_b32 s52, v254, 42
	v_readlane_b32 s53, v254, 43
	v_cmp_gt_i32_e32 vcc, s68, v16
	v_mov_b32_e32 v8, s21
	v_mov_b32_e32 v9, s53
	v_mov_b32_e32 v10, s20
	v_mov_b32_e32 v11, s52
	v_min_i32_e32 v40, 0x4000, v16
	v_readlane_b32 s12, v254, 13
	v_readlane_b32 s13, v254, 14
	v_cndmask_b32_e32 v9, v8, v9, vcc
	v_cndmask_b32_e32 v8, v10, v11, vcc
	v_ashrrev_i32_e32 v10, 13, v40
	s_mul_i32 s3, s24, 3
	v_add_u32_e32 v4, 0xffffc000, v16
	v_readlane_b32 s10, v254, 11
	v_readlane_b32 s11, v254, 12
	v_mov_b64_e32 v[6:7], s[12:13]
	v_add_u32_e32 v40, s3, v10
	v_cndmask_b32_e32 v5, 0, v17, vcc
	v_cndmask_b32_e32 v4, v4, v16, vcc
	v_mad_i64_i32 v[6:7], s[10:11], v40, s67, v[6:7]
	v_lshlrev_b64 v[4:5], 12, v[4:5]
	s_mov_b64 s[10:11], 0x5000
	v_lshlrev_b32_e32 v192, 2, v18
	v_lshl_add_u64 v[4:5], v[8:9], 0, v[4:5]
	v_lshl_add_u64 v[56:57], v[6:7], 0, s[10:11]
	global_load_dwordx4 v[0:3], v[26:27], off
	v_lshl_add_u64 v[54:55], v[4:5], 0, v[192:193]
	v_lshl_add_u64 v[8:9], v[56:57], 0, v[192:193]
	global_load_dwordx4 v[4:7], v[54:55], off
	s_andn2_b64 vcc, exec, s[38:39]
	global_load_dwordx4 v[8:11], v[8:9], off
	v_lshl_add_u64 v[96:97], v[56:57], 0, v[192:193]
	global_load_dwordx4 v[100:103], v[54:55], off offset:1024
	global_load_dwordx4 v[112:115], v[26:27], off offset:1024
	global_load_dwordx4 v[124:127], v[96:97], off offset:1024
	global_load_dwordx4 v[104:107], v[54:55], off offset:2048
	global_load_dwordx4 v[116:119], v[26:27], off offset:2048
	global_load_dwordx4 v[128:131], v[96:97], off offset:2048
	global_load_dwordx4 v[120:123], v[26:27], off offset:3072
	global_load_dwordx4 v[108:111], v[54:55], off offset:3072
	global_load_dwordx4 v[132:135], v[96:97], off offset:3072
	v_readlane_b32 s9, v254, 10
	v_readlane_b32 s14, v254, 15
	v_readlane_b32 s15, v254, 16
	v_readlane_b32 s16, v254, 17
	v_readlane_b32 s17, v254, 18
	v_readlane_b32 s18, v254, 19
	v_readlane_b32 s19, v254, 20
	v_readlane_b32 s22, v254, 23
	v_readlane_b32 s23, v254, 24
	v_readlane_b32 s49, v254, 39
	v_readlane_b32 s50, v254, 40
	v_readlane_b32 s51, v254, 41
	v_readlane_b32 s54, v254, 44
	v_readlane_b32 s55, v254, 45
	v_readlane_b32 s56, v254, 46
	v_readlane_b32 s57, v254, 47
	v_readlane_b32 s58, v254, 48
	v_readlane_b32 s59, v254, 49
	v_readlane_b32 s60, v254, 50
	v_readlane_b32 s61, v254, 51
	v_readlane_b32 s62, v254, 52
	v_readlane_b32 s63, v254, 53
	s_waitcnt vmcnt(15)
	v_lshlrev_b32_e32 v52, 16, v12
	v_and_b32_e32 v53, 0xffff0000, v12
	s_waitcnt vmcnt(13)
	v_lshlrev_b32_e32 v62, 16, v36
	v_and_b32_e32 v63, 0xffff0000, v36
	s_waitcnt vmcnt(12)
	v_and_b32_e32 v67, 0xffff0000, v38
	v_and_b32_e32 v69, 0xffff0000, v14
	v_lshlrev_b32_e32 v50, 16, v13
	v_and_b32_e32 v51, 0xffff0000, v13
	v_and_b32_e32 v59, 0xffff0000, v15
	v_lshlrev_b32_e32 v58, 16, v15
	v_lshlrev_b32_e32 v60, 16, v37
	v_and_b32_e32 v61, 0xffff0000, v37
	v_lshlrev_b32_e32 v64, 16, v39
	v_and_b32_e32 v65, 0xffff0000, v39
	v_lshlrev_b32_e32 v66, 16, v38
	v_lshlrev_b32_e32 v68, 16, v14
	v_pk_mul_f32 v[14:15], v[52:53], v[52:53]
	v_pk_mul_f32 v[38:39], v[62:63], v[62:63]
	v_mov_b32_e32 v70, v67
	v_mov_b32_e32 v71, v69
	v_pk_mul_f32 v[12:13], v[50:51], v[50:51]
	v_pk_mul_f32 v[36:37], v[60:61], v[60:61]
	v_mov_b32_e32 v46, v66
	v_mov_b32_e32 v47, v68
	v_pk_mul_f32 v[70:71], v[70:71], v[70:71]
	v_add_f32_e32 v38, v38, v39
	v_add_f32_e32 v39, v14, v15
	v_mov_b32_e32 v42, v64
	v_mov_b32_e32 v43, v58
	v_pk_fma_f32 v[14:15], v[46:47], v[46:47], v[70:71]
	v_add_f32_e32 v36, v36, v38
	v_add_f32_e32 v12, v12, v39
	v_mov_b32_e32 v44, v65
	v_mov_b32_e32 v45, v59
	v_pk_fma_f32 v[14:15], v[42:43], v[42:43], v[14:15]
	v_add_f32_e32 v36, v37, v36
	v_add_f32_e32 v37, v13, v12
	v_pk_fma_f32 v[12:13], v[44:45], v[44:45], v[14:15]
	v_add_f32_e32 v14, v37, v36
	v_add_f32_e32 v12, v14, v12
	v_add_f32_e32 v12, v12, v13
	v_lshlrev_b32_e32 v42, 2, v20
	v_mov_b32_e32 v43, v193
	s_nop 0
	v_lshlrev_b32_e32 v38, 2, v22
	s_waitcnt lgkmcnt(0)
	v_mov_b32_e32 v13, v12
	s_nop 1
	v_permlane32_swap_b32_e32 v13, v12
	v_add_f32_e32 v12, v12, v13
	v_mov_b32_e32 v39, v193
	v_lshlrev_b32_e32 v36, 2, v24
	v_mov_b32_e32 v37, v193
	v_mov_b32_e32 v13, v12
	s_nop 1
	v_permlane16_swap_b32_e32 v13, v12
	v_add_f32_e32 v12, v12, v13
	s_nop 1
	v_add_f32_dpp v12, v12, v12 row_ror:8 row_mask:0xf bank_mask:0xf
	s_nop 1
	v_add_f32_dpp v12, v12, v12 row_ror:4 row_mask:0xf bank_mask:0xf
	s_nop 1
	v_add_f32_dpp v12, v12, v12 row_ror:2 row_mask:0xf bank_mask:0xf
	s_nop 1
	v_add_f32_dpp v12, v12, v12 row_ror:1 row_mask:0xf bank_mask:0xf
	v_fmamk_f32 v12, v12, 0x3a800000, v221
	v_rsq_f32_e32 v70, v12
	s_nop 0
	v_pk_mul_f32 v[12:13], v[70:71], v[52:53] op_sel_hi:[0,1]
	v_pk_mul_f32 v[14:15], v[70:71], v[50:51] op_sel_hi:[0,1]
	s_waitcnt vmcnt(11)
	v_pk_mul_f32 v[0:1], v[0:1], v[12:13]
	v_pk_mul_f32 v[2:3], v[2:3], v[14:15]
	s_waitcnt vmcnt(9)
	v_pk_fma_f32 v[12:13], v[8:9], v[0:1], v[4:5]
	v_pk_fma_f32 v[14:15], v[10:11], v[2:3], v[6:7]
	global_store_dwordx4 v[54:55], v[12:15], off
	s_nop 0
	v_lshl_add_u64 v[4:5], v[56:57], 0, v[42:43]
	s_nop 0
	v_pk_mul_f32 v[8:9], v[70:71], v[62:63] op_sel_hi:[0,1]
	v_pk_mul_f32 v[10:11], v[70:71], v[60:61] op_sel_hi:[0,1]
	s_nop 0
	v_pk_mul_f32 v[60:61], v[70:71], v[66:67] op_sel_hi:[0,1]
	v_pk_mul_f32 v[62:63], v[70:71], v[64:65] op_sel_hi:[0,1]
	v_pk_mul_f32 v[58:59], v[70:71], v[58:59] op_sel_hi:[0,1]
	s_waitcnt vmcnt(8)
	v_pk_mul_f32 v[0:1], v[112:113], v[8:9]
	v_pk_mul_f32 v[2:3], v[114:115], v[10:11]
	s_waitcnt vmcnt(7)
	v_pk_fma_f32 v[8:9], v[124:125], v[0:1], v[100:101]
	v_pk_fma_f32 v[10:11], v[126:127], v[2:3], v[102:103]
	global_store_dwordx4 v[54:55], v[8:11], off offset:1024
	s_nop 0
	v_lshl_add_u64 v[4:5], v[56:57], 0, v[38:39]
	s_nop 0
	s_waitcnt vmcnt(6)
	v_pk_mul_f32 v[0:1], v[116:117], v[60:61]
	v_pk_mul_f32 v[2:3], v[118:119], v[62:63]
	s_waitcnt vmcnt(5)
	v_pk_fma_f32 v[4:5], v[128:129], v[0:1], v[104:105]
	v_pk_fma_f32 v[6:7], v[130:131], v[2:3], v[106:107]
	global_store_dwordx4 v[54:55], v[4:7], off offset:2048
	s_nop 0
	v_lshl_add_u64 v[50:51], v[56:57], 0, v[36:37]
	s_nop 0
	v_pk_mul_f32 v[56:57], v[70:71], v[68:69] op_sel_hi:[0,1]
	s_nop 0
	s_waitcnt vmcnt(5)
	v_pk_mul_f32 v[0:1], v[56:57], v[120:121]
	v_pk_mul_f32 v[2:3], v[58:59], v[122:123]
	s_waitcnt vmcnt(3)
	v_pk_fma_f32 v[0:1], v[132:133], v[0:1], v[108:109]
	v_pk_fma_f32 v[2:3], v[134:135], v[2:3], v[110:111]
	global_store_dwordx4 v[54:55], v[0:3], off offset:3072
	s_cbranch_vccnz .LBB0_27
	v_pk_mul_f32 v[44:45], v[12:13], v[12:13]
	v_pk_mul_f32 v[46:47], v[14:15], v[14:15]
	v_add_f32_e32 v44, v44, v45
	v_add_f32_e32 v44, v46, v44
	v_pk_mul_f32 v[50:51], v[8:9], v[8:9]
	v_add_f32_e32 v44, v47, v44
	v_add_f32_e32 v44, v50, v44
	v_pk_mul_f32 v[52:53], v[10:11], v[10:11]
	v_add_f32_e32 v44, v51, v44
	v_add_f32_e32 v44, v52, v44
	v_pk_mul_f32 v[54:55], v[4:5], v[4:5]
	v_add_f32_e32 v44, v53, v44
	v_add_f32_e32 v44, v54, v44
	v_pk_mul_f32 v[56:57], v[6:7], v[6:7]
	v_add_f32_e32 v44, v55, v44
	v_add_f32_e32 v44, v56, v44
	v_pk_mul_f32 v[58:59], v[0:1], v[0:1]
	v_add_f32_e32 v44, v57, v44
	v_add_f32_e32 v44, v58, v44
	v_pk_mul_f32 v[60:61], v[2:3], v[2:3]
	v_add_f32_e32 v44, v59, v44
	v_add_f32_e32 v44, v60, v44
	v_add_f32_e32 v44, v61, v44
	v_readlane_b32 s8, v254, 9
	v_readlane_b32 s12, v254, 13
	v_readlane_b32 s13, v254, 14
	v_add_u32_e32 v40, 3, v40
	s_waitcnt lgkmcnt(0)
	v_mov_b32_e32 v45, v44
	s_nop 1
	v_permlane32_swap_b32_e32 v45, v44
	v_add_f32_e32 v44, v44, v45
	v_readlane_b32 s10, v254, 11
	v_readlane_b32 s11, v254, 12
	global_load_dwordx4 v[50:53], v[28:29], off
	v_readlane_b32 s9, v254, 10
	v_mov_b32_e32 v45, v44
	s_nop 1
	v_permlane16_swap_b32_e32 v45, v44
	v_add_f32_e32 v44, v44, v45
	v_readlane_b32 s14, v254, 15
	v_readlane_b32 s15, v254, 16
	v_readlane_b32 s16, v254, 17
	v_readlane_b32 s17, v254, 18
	s_nop 1
	v_add_f32_dpp v44, v44, v44 row_ror:8 row_mask:0xf bank_mask:0xf
	v_readlane_b32 s18, v254, 19
	v_readlane_b32 s19, v254, 20
	v_readlane_b32 s20, v254, 21
	v_readlane_b32 s21, v254, 22
	s_nop 1
	v_add_f32_dpp v44, v44, v44 row_ror:4 row_mask:0xf bank_mask:0xf
	v_readlane_b32 s22, v254, 23
	v_readlane_b32 s23, v254, 24
	s_nop 1
	v_add_f32_dpp v44, v44, v44 row_ror:2 row_mask:0xf bank_mask:0xf
	s_nop 1
	v_add_f32_dpp v49, v44, v44 row_ror:1 row_mask:0xf bank_mask:0xf
	v_mov_b64_e32 v[44:45], s[12:13]
	v_mad_i64_i32 v[44:45], s[10:11], v40, s67, v[44:45]
	v_lshl_add_u64 v[46:47], v[44:45], 0, s[34:35]
	v_lshl_add_u64 v[54:55], v[46:47], 0, v[192:193]
	global_load_dwordx4 v[54:57], v[54:55], off
	v_lshl_add_u64 v[44:45], v[44:45], 0, v[192:193]
	global_load_dwordx4 v[58:61], v[44:45], off
	v_lshl_add_u64 v[98:99], v[46:47], 0, v[192:193]
	global_load_dwordx4 v[140:143], v[28:29], off offset:1024
	global_load_dwordx4 v[152:155], v[98:99], off offset:1024
	global_load_dwordx4 v[164:167], v[44:45], off offset:1024
	global_load_dwordx4 v[144:147], v[28:29], off offset:2048
	global_load_dwordx4 v[156:159], v[98:99], off offset:2048
	global_load_dwordx4 v[168:171], v[44:45], off offset:2048
	global_load_dwordx4 v[148:151], v[28:29], off offset:3072
	global_load_dwordx4 v[160:163], v[98:99], off offset:3072
	global_load_dwordx4 v[172:175], v[44:45], off offset:3072
	v_fmamk_f32 v40, v49, 0x3a800000, v221
	v_rsq_f32_e32 v40, v40
	s_nop 0
	v_pk_mul_f32 v[12:13], v[12:13], v[40:41] op_sel_hi:[1,0]
	v_pk_mul_f32 v[14:15], v[14:15], v[40:41] op_sel_hi:[1,0]
	v_pk_mul_f32 v[8:9], v[8:9], v[40:41] op_sel_hi:[1,0]
	v_pk_mul_f32 v[10:11], v[10:11], v[40:41] op_sel_hi:[1,0]
	v_pk_mul_f32 v[4:5], v[4:5], v[40:41] op_sel_hi:[1,0]
	v_pk_mul_f32 v[6:7], v[6:7], v[40:41] op_sel_hi:[1,0]
	v_pk_mul_f32 v[0:1], v[0:1], v[40:41] op_sel_hi:[1,0]
	v_pk_mul_f32 v[2:3], v[2:3], v[40:41] op_sel_hi:[1,0]
	s_waitcnt vmcnt(11)
	v_pk_mul_f32 v[12:13], v[50:51], v[12:13]
	v_pk_mul_f32 v[14:15], v[52:53], v[14:15]
	s_waitcnt vmcnt(10)
	v_pk_add_f32 v[50:51], v[54:55], 1.0 op_sel_hi:[1,0]
	s_waitcnt vmcnt(9)
	v_pk_fma_f32 v[12:13], v[50:51], v[12:13], v[58:59]
	v_pk_add_f32 v[50:51], v[56:57], 1.0 op_sel_hi:[1,0]
	s_nop 0
	v_pk_fma_f32 v[14:15], v[50:51], v[14:15], v[60:61]
	v_cvt_pk_bf16_f32 v50, v12, v13
	v_cvt_pk_bf16_f32 v51, v14, v15
	v_lshl_add_u64 v[12:13], v[34:35], 0, v[30:31]
	global_store_dwordx2 v[12:13], v[50:51], off
	s_nop 0
	v_lshl_add_u64 v[14:15], v[46:47], 0, v[42:43]
	s_nop 0
	s_nop 0
	s_waitcnt vmcnt(9)
	v_pk_mul_f32 v[8:9], v[8:9], v[140:141]
	s_waitcnt vmcnt(8)
	v_pk_add_f32 v[14:15], v[152:153], 1.0 op_sel_hi:[1,0]
	v_pk_mul_f32 v[10:11], v[10:11], v[142:143]
	s_waitcnt vmcnt(7)
	v_pk_fma_f32 v[8:9], v[8:9], v[14:15], v[164:165]
	v_pk_add_f32 v[14:15], v[154:155], 1.0 op_sel_hi:[1,0]
	v_cvt_pk_bf16_f32 v8, v8, v9
	v_pk_fma_f32 v[10:11], v[10:11], v[14:15], v[166:167]
	v_lshl_add_u64 v[14:15], v[46:47], 0, v[38:39]
	v_cvt_pk_bf16_f32 v9, v10, v11
	global_store_dwordx2 v[12:13], v[8:9], off offset:512
	s_nop 0
	s_nop 0
	s_nop 0
	s_nop 0
	s_waitcnt vmcnt(7)
	v_pk_mul_f32 v[4:5], v[4:5], v[144:145]
	s_waitcnt vmcnt(6)
	v_pk_add_f32 v[8:9], v[156:157], 1.0 op_sel_hi:[1,0]
	v_pk_mul_f32 v[6:7], v[6:7], v[146:147]
	s_waitcnt vmcnt(5)
	v_pk_fma_f32 v[4:5], v[4:5], v[8:9], v[168:169]
	v_pk_add_f32 v[8:9], v[158:159], 1.0 op_sel_hi:[1,0]
	v_cvt_pk_bf16_f32 v4, v4, v5
	v_pk_fma_f32 v[6:7], v[6:7], v[8:9], v[170:171]
	v_lshl_add_u64 v[8:9], v[46:47], 0, v[36:37]
	v_cvt_pk_bf16_f32 v5, v6, v7
	global_store_dwordx2 v[12:13], v[4:5], off offset:1024
	s_nop 0
	s_nop 0
	s_nop 0
	s_nop 0
	s_nop 0
	s_waitcnt vmcnt(5)
	v_pk_mul_f32 v[0:1], v[0:1], v[148:149]
	s_waitcnt vmcnt(4)
	v_pk_add_f32 v[4:5], v[160:161], 1.0 op_sel_hi:[1,0]
	v_pk_mul_f32 v[2:3], v[2:3], v[150:151]
	s_waitcnt vmcnt(3)
	v_pk_fma_f32 v[0:1], v[0:1], v[4:5], v[172:173]
	v_pk_add_f32 v[4:5], v[162:163], 1.0 op_sel_hi:[1,0]
	v_cvt_pk_bf16_f32 v0, v0, v1
	v_pk_fma_f32 v[2:3], v[2:3], v[4:5], v[174:175]
	s_nop 0
	v_cvt_pk_bf16_f32 v1, v2, v3
	global_store_dwordx2 v[12:13], v[0:1], off offset:1536
	s_branch .LBB0_27

.LBB0_71:
	v_readlane_b32 s8, v253, 56
	v_readlane_b32 s12, v253, 60
	v_cmp_gt_i32_e64 s[0:1], s3, v24
	v_mov_b32_e32 v3, s8
	s_mov_b32 s8, s54
	v_readlane_b32 s48, v254, 9
	v_readlane_b32 s9, v253, 57
	v_readlane_b32 s10, v253, 58
	v_readlane_b32 s11, v253, 59
	v_readlane_b32 s13, v253, 61
	v_readlane_b32 s14, v253, 62
	v_readlane_b32 s15, v253, 63
	v_readlane_b32 s16, v254, 0
	v_readlane_b32 s17, v254, 1
	v_readlane_b32 s18, v254, 2
	v_readlane_b32 s19, v254, 3
	v_readlane_b32 s20, v254, 4
	v_readlane_b32 s21, v254, 5
	v_readlane_b32 s22, v254, 6
	v_readlane_b32 s23, v254, 7
	v_mov_b32_e32 v2, s12
	v_readlane_b32 s54, v254, 15
	v_cndmask_b32_e64 v2, v2, v3, s[0:1]
	v_mov_b32_e32 v3, s13
	v_mov_b32_e32 v4, s9
	s_mov_b32 s54, s8
	v_readlane_b32 s8, v254, 38
	v_readlane_b32 s61, v254, 22
	v_readlane_b32 s13, v254, 43
	v_cndmask_b32_e64 v3, v3, v4, s[0:1]
	v_readlane_b32 s60, v254, 21
	v_mov_b32_e32 v4, s61
	v_readlane_b32 s12, v254, 42
	v_mov_b32_e32 v5, s13
	v_add_u32_e32 v0, 0xffffc000, v24
	v_cndmask_b32_e64 v17, v4, v5, s[0:1]
	v_mov_b32_e32 v4, s60
	v_mov_b32_e32 v5, s12
	v_cndmask_b32_e64 v1, 0, v25, s[0:1]
	v_cndmask_b32_e64 v0, v0, v24, s[0:1]
	v_cndmask_b32_e64 v16, v4, v5, s[0:1]
	v_cndmask_b32_e32 v3, v17, v3, vcc
	v_cndmask_b32_e32 v2, v16, v2, vcc
	v_lshlrev_b64 v[18:19], 12, v[0:1]
	v_lshl_add_u64 v[0:1], v[2:3], 0, v[18:19]
	v_min_i32_e32 v2, 0x4000, v24
	v_readlane_b32 s52, v254, 13
	v_readlane_b32 s53, v254, 14
	v_ashrrev_i32_e32 v2, 13, v2
	s_mul_i32 s0, s54, 3
	v_add_u32_e32 v4, s0, v2
	v_mov_b64_e32 v[2:3], s[52:53]
	v_mad_i64_i32 v[42:43], s[0:1], v4, s67, v[2:3]
	v_lshl_add_u64 v[4:5], v[32:33], 0, v[30:31]
	v_lshl_add_u64 v[6:7], v[0:1], 0, v[192:193]
	global_load_dwordx2 v[54:55], v[4:5], off
	global_load_dwordx4 v[12:15], v[6:7], off
	global_load_dwordx2 v[58:59], v[4:5], off offset:512
	global_load_dwordx4 v[8:11], v[6:7], off offset:1024
	global_load_dwordx2 v[20:21], v[4:5], off offset:1024
	global_load_dwordx4 v[0:3], v[6:7], off offset:2048
	global_load_dwordx2 v[22:23], v[4:5], off offset:1536
	s_nop 0
	global_load_dwordx4 v[4:7], v[6:7], off offset:3072
	v_lshl_add_u64 v[96:97], v[42:43], 0, v[192:193]
	s_mov_b64 s[0:1], 0x2000
	v_lshl_add_u64 v[98:99], v[96:97], 0, s[0:1]
	s_mov_b64 s[0:1], 0x3000
	v_lshl_add_u64 v[100:101], v[96:97], 0, s[0:1]
	s_mov_b64 s[0:1], 0x4000
	v_lshl_add_u64 v[102:103], v[96:97], 0, s[0:1]
	global_load_dwordx4 v[104:107], v[98:99], off
	global_load_dwordx4 v[120:123], v[26:27], off
	global_load_dwordx4 v[108:111], v[98:99], off offset:1024
	global_load_dwordx4 v[124:127], v[26:27], off offset:1024
	global_load_dwordx4 v[112:115], v[98:99], off offset:2048
	global_load_dwordx4 v[128:131], v[26:27], off offset:2048
	global_load_dwordx4 v[116:119], v[98:99], off offset:3072
	global_load_dwordx4 v[132:135], v[26:27], off offset:3072
	global_load_dwordx4 v[136:139], v[102:103], off
	global_load_dwordx4 v[152:155], v[100:101], off
	global_load_dwordx4 v[168:171], v[28:29], off
	global_load_dwordx4 v[172:175], v[28:29], off offset:1024
	global_load_dwordx4 v[140:143], v[102:103], off offset:1024
	global_load_dwordx4 v[156:159], v[100:101], off offset:1024
	global_load_dwordx4 v[176:179], v[28:29], off offset:2048
	global_load_dwordx4 v[144:147], v[102:103], off offset:2048
	global_load_dwordx4 v[160:163], v[100:101], off offset:2048
	global_load_dwordx4 v[180:183], v[28:29], off offset:3072
	global_load_dwordx4 v[148:151], v[102:103], off offset:3072
	global_load_dwordx4 v[164:167], v[100:101], off offset:3072
	s_mov_b64 s[0:1], 0x2000
	v_lshl_add_u64 v[52:53], v[42:43], 0, s[0:1]
	v_lshl_add_u64 v[72:73], v[16:17], 0, v[18:19]
	v_lshl_add_u64 v[16:17], v[52:53], 0, v[192:193]
	v_mov_b32_e32 v37, v193
	s_mov_b64 s[0:1], 0x4000
	v_lshl_add_u64 v[24:25], v[24:25], 0, s[40:41]
	v_lshl_add_u64 v[32:33], v[32:33], 0, s[42:43]
	v_readlane_b32 s49, v254, 10
	v_readlane_b32 s50, v254, 11
	v_readlane_b32 s51, v254, 12
	v_readlane_b32 s55, v254, 16
	v_readlane_b32 s56, v254, 17
	v_readlane_b32 s57, v254, 18
	v_readlane_b32 s58, v254, 19
	v_readlane_b32 s59, v254, 20
	v_readlane_b32 s62, v254, 23
	v_readlane_b32 s63, v254, 24
	v_readlane_b32 s9, v254, 39
	v_readlane_b32 s10, v254, 40
	v_readlane_b32 s11, v254, 41
	v_readlane_b32 s14, v254, 44
	v_readlane_b32 s15, v254, 45
	v_readlane_b32 s16, v254, 46
	v_readlane_b32 s17, v254, 47
	v_readlane_b32 s18, v254, 48
	v_readlane_b32 s19, v254, 49
	v_readlane_b32 s20, v254, 50
	v_readlane_b32 s21, v254, 51
	v_readlane_b32 s22, v254, 52
	v_readlane_b32 s23, v254, 53
	s_waitcnt vmcnt(27)
	v_lshlrev_b32_e32 v62, 16, v54
	v_and_b32_e32 v63, 0xffff0000, v54
	s_waitcnt vmcnt(25)
	v_lshlrev_b32_e32 v76, 16, v58
	v_and_b32_e32 v77, 0xffff0000, v58
	s_waitcnt vmcnt(23)
	v_and_b32_e32 v50, 0xffff0000, v20
	v_lshlrev_b32_e32 v48, 16, v20
	s_waitcnt vmcnt(21)
	v_and_b32_e32 v51, 0xffff0000, v22
	v_lshlrev_b32_e32 v49, 16, v22
	v_lshlrev_b32_e32 v44, 16, v21
	v_and_b32_e32 v46, 0xffff0000, v21
	v_pk_mul_f32 v[20:21], v[50:51], v[50:51]
	v_lshlrev_b32_e32 v45, 16, v23
	v_pk_fma_f32 v[20:21], v[48:49], v[48:49], v[20:21]
	v_and_b32_e32 v47, 0xffff0000, v23
	v_pk_fma_f32 v[20:21], v[44:45], v[44:45], v[20:21]
	v_pk_mul_f32 v[74:75], v[62:63], v[62:63]
	v_pk_fma_f32 v[56:57], v[46:47], v[46:47], v[20:21]
	s_nop 0
	s_nop 0
	s_nop 0
	v_lshlrev_b32_e32 v60, 16, v55
	v_and_b32_e32 v61, 0xffff0000, v55
	v_pk_mul_f32 v[78:79], v[76:77], v[76:77]
	v_lshlrev_b32_e32 v80, 16, v59
	v_and_b32_e32 v81, 0xffff0000, v59
	v_pk_mul_f32 v[64:65], v[60:61], v[60:61]
	v_pk_mul_f32 v[58:59], v[80:81], v[80:81]
	v_add_f32_e32 v39, v78, v79
	v_add_f32_e32 v41, v74, v75
	v_add_f32_e32 v39, v58, v39
	v_add_f32_e32 v41, v64, v41
	v_add_f32_e32 v39, v59, v39
	v_add_f32_e32 v41, v65, v41
	v_add_f32_e32 v39, v41, v39
	v_add_f32_e32 v39, v39, v56
	v_add_f32_e32 v39, v39, v57
	v_lshl_add_u64 v[54:55], v[72:73], 0, v[192:193]
	v_lshl_add_u64 v[72:73], v[52:53], 0, v[36:37]
	s_waitcnt lgkmcnt(0)
	v_mov_b32_e32 v41, v39
	s_nop 1
	v_permlane32_swap_b32_e32 v41, v39
	v_add_f32_e32 v39, v39, v41
	v_mov_b32_e32 v41, v39
	s_nop 1
	v_permlane16_swap_b32_e32 v41, v39
	v_add_f32_e32 v39, v39, v41
	s_nop 1
	v_add_f32_dpp v39, v39, v39 row_ror:8 row_mask:0xf bank_mask:0xf
	s_nop 1
	v_add_f32_dpp v39, v39, v39 row_ror:4 row_mask:0xf bank_mask:0xf
	s_nop 1
	v_add_f32_dpp v39, v39, v39 row_ror:2 row_mask:0xf bank_mask:0xf
	s_nop 1
	v_add_f32_dpp v39, v39, v39 row_ror:1 row_mask:0xf bank_mask:0xf
	v_fmamk_f32 v39, v39, 0x3a800000, v221
	v_rsq_f32_e32 v56, v39
	v_mov_b32_e32 v39, v193
	v_mov_b32_e32 v41, v193
	v_pk_mul_f32 v[58:59], v[56:57], v[62:63] op_sel_hi:[0,1]
	v_pk_mul_f32 v[62:63], v[56:57], v[76:77] op_sel_hi:[0,1]
	s_waitcnt vmcnt(18)
	v_pk_mul_f32 v[20:21], v[120:121], v[58:59]
	s_nop 0
	v_pk_fma_f32 v[12:13], v[104:105], v[20:21], v[12:13]
	v_pk_mul_f32 v[20:21], v[56:57], v[60:61] op_sel_hi:[0,1]
	v_pk_mul_f32 v[20:21], v[122:123], v[20:21]
	v_pk_mul_f32 v[16:17], v[12:13], v[12:13]
	v_pk_fma_f32 v[14:15], v[106:107], v[20:21], v[14:15]
	global_store_dwordx4 v[54:55], v[12:15], off
	s_nop 0
	s_nop 0
	v_mov_b32_e32 v72, v48
	v_mov_b32_e32 v73, v50
	v_pk_mul_f32 v[72:73], v[56:57], v[72:73] op_sel_hi:[0,1]
	v_pk_mul_f32 v[18:19], v[14:15], v[14:15]
	v_add_f32_e32 v16, v16, v17
	v_add_f32_e32 v16, v18, v16
	v_add_f32_e32 v16, v19, v16
	v_mov_b32_e32 v50, v49
	v_pk_mul_f32 v[48:49], v[56:57], v[50:51] op_sel_hi:[0,1]
	s_waitcnt vmcnt(17)
	v_pk_mul_f32 v[58:59], v[124:125], v[62:63]
	s_nop 0
	v_pk_fma_f32 v[8:9], v[108:109], v[58:59], v[8:9]
	v_pk_mul_f32 v[20:21], v[56:57], v[80:81] op_sel_hi:[0,1]
	v_pk_mul_f32 v[20:21], v[126:127], v[20:21]
	v_pk_mul_f32 v[62:63], v[8:9], v[8:9]
	v_pk_fma_f32 v[10:11], v[110:111], v[20:21], v[10:11]
	global_store_dwordx4 v[54:55], v[8:11], off offset:1024
	v_lshl_add_u64 v[20:21], v[52:53], 0, v[38:39]
	s_nop 0
	s_nop 0
	s_nop 0
	v_add_f32_e32 v16, v62, v16
	v_pk_mul_f32 v[64:65], v[10:11], v[10:11]
	v_add_f32_e32 v16, v63, v16
	v_add_f32_e32 v16, v64, v16
	v_add_f32_e32 v16, v65, v16
	s_waitcnt vmcnt(16)
	v_pk_mul_f32 v[58:59], v[128:129], v[72:73]
	s_nop 0
	v_pk_fma_f32 v[0:1], v[112:113], v[58:59], v[0:1]
	v_mov_b32_e32 v20, v44
	v_mov_b32_e32 v21, v46
	v_pk_mul_f32 v[20:21], v[56:57], v[20:21] op_sel_hi:[0,1]
	v_pk_mul_f32 v[20:21], v[130:131], v[20:21]
	v_pk_mul_f32 v[72:73], v[0:1], v[0:1]
	v_pk_fma_f32 v[2:3], v[114:115], v[20:21], v[2:3]
	global_store_dwordx4 v[54:55], v[0:3], off offset:2048
	v_lshl_add_u64 v[20:21], v[52:53], 0, v[40:41]
	s_nop 0
	s_nop 0
	s_nop 0
	v_add_f32_e32 v16, v72, v16
	v_pk_mul_f32 v[74:75], v[2:3], v[2:3]
	v_mov_b32_e32 v46, v45
	v_add_f32_e32 v16, v73, v16
	v_pk_mul_f32 v[44:45], v[56:57], v[46:47] op_sel_hi:[0,1]
	v_add_f32_e32 v16, v74, v16
	v_add_f32_e32 v16, v75, v16
	s_waitcnt vmcnt(15)
	v_pk_mul_f32 v[48:49], v[48:49], v[132:133]
	s_nop 0
	v_pk_fma_f32 v[4:5], v[116:117], v[48:49], v[4:5]
	v_pk_mul_f32 v[44:45], v[44:45], v[134:135]
	v_pk_mul_f32 v[20:21], v[4:5], v[4:5]
	v_pk_fma_f32 v[6:7], v[118:119], v[44:45], v[6:7]
	v_add_f32_e32 v16, v20, v16
	v_pk_mul_f32 v[22:23], v[6:7], v[6:7]
	v_add_f32_e32 v16, v21, v16
	v_add_f32_e32 v16, v22, v16
	v_add_f32_e32 v16, v23, v16
	v_lshl_add_u64 v[44:45], v[42:43], 0, s[0:1]
	s_mov_b64 s[0:1], 0x3000
	global_store_dwordx4 v[54:55], v[4:7], off offset:3072
	v_lshl_add_u64 v[22:23], v[42:43], 0, s[0:1]
	s_waitcnt lgkmcnt(0)
	v_mov_b32_e32 v17, v16
	s_nop 1
	v_permlane32_swap_b32_e32 v17, v16
	v_add_f32_e32 v16, v16, v17
	v_lshl_add_u64 v[42:43], v[44:45], 0, v[192:193]
	s_nop 0
	v_lshl_add_u64 v[42:43], v[22:23], 0, v[192:193]
	s_nop 0
	v_mov_b32_e32 v17, v16
	s_nop 1
	v_permlane16_swap_b32_e32 v17, v16
	v_add_f32_e32 v16, v16, v17
	v_lshl_add_u64 v[42:43], v[34:35], 0, v[30:31]
	v_cmp_le_i32_e64 s[0:1], s2, v24
	v_lshl_add_u64 v[34:35], v[34:35], 0, s[42:43]
	s_or_b64 s[44:45], s[0:1], s[44:45]
	s_nop 1
	v_add_f32_dpp v16, v16, v16 row_ror:8 row_mask:0xf bank_mask:0xf
	s_nop 1
	v_add_f32_dpp v16, v16, v16 row_ror:4 row_mask:0xf bank_mask:0xf
	s_nop 1
	v_add_f32_dpp v16, v16, v16 row_ror:2 row_mask:0xf bank_mask:0xf
	s_nop 1
	v_add_f32_dpp v16, v16, v16 row_ror:1 row_mask:0xf bank_mask:0xf
	v_fmamk_f32 v16, v16, 0x3a800000, v221
	v_rsq_f32_e32 v20, v16
	s_nop 0
	v_pk_mul_f32 v[12:13], v[12:13], v[20:21] op_sel_hi:[1,0]
	v_pk_mul_f32 v[14:15], v[14:15], v[20:21] op_sel_hi:[1,0]
	v_pk_mul_f32 v[8:9], v[8:9], v[20:21] op_sel_hi:[1,0]
	v_pk_mul_f32 v[10:11], v[10:11], v[20:21] op_sel_hi:[1,0]
	v_pk_mul_f32 v[0:1], v[0:1], v[20:21] op_sel_hi:[1,0]
	v_pk_mul_f32 v[2:3], v[2:3], v[20:21] op_sel_hi:[1,0]
	v_pk_mul_f32 v[4:5], v[4:5], v[20:21] op_sel_hi:[1,0]
	s_waitcnt vmcnt(13)
	v_pk_mul_f32 v[12:13], v[168:169], v[12:13]
	v_pk_add_f32 v[16:17], v[136:137], 1.0 op_sel_hi:[1,0]
	v_pk_mul_f32 v[14:15], v[170:171], v[14:15]
	v_pk_fma_f32 v[12:13], v[16:17], v[12:13], v[152:153]
	v_pk_add_f32 v[16:17], v[138:139], 1.0 op_sel_hi:[1,0]
	v_cvt_pk_bf16_f32 v12, v12, v13
	v_pk_fma_f32 v[14:15], v[16:17], v[14:15], v[154:155]
	v_lshl_add_u64 v[16:17], v[44:45], 0, v[36:37]
	v_cvt_pk_bf16_f32 v13, v14, v15
	global_store_dwordx2 v[42:43], v[12:13], off
	s_nop 0
	v_lshl_add_u64 v[46:47], v[22:23], 0, v[36:37]
	s_nop 0
	s_waitcnt vmcnt(13)
	v_pk_mul_f32 v[8:9], v[172:173], v[8:9]
	s_nop 0
	s_waitcnt vmcnt(12)
	v_pk_add_f32 v[12:13], v[140:141], 1.0 op_sel_hi:[1,0]
	v_pk_mul_f32 v[10:11], v[174:175], v[10:11]
	v_lshl_add_u64 v[16:17], v[22:23], 0, v[38:39]
	s_waitcnt vmcnt(11)
	v_pk_fma_f32 v[8:9], v[12:13], v[8:9], v[156:157]
	v_pk_add_f32 v[12:13], v[142:143], 1.0 op_sel_hi:[1,0]
	v_cvt_pk_bf16_f32 v8, v8, v9
	v_pk_fma_f32 v[10:11], v[12:13], v[10:11], v[158:159]
	v_lshl_add_u64 v[12:13], v[44:45], 0, v[38:39]
	v_cvt_pk_bf16_f32 v9, v10, v11
	global_store_dwordx2 v[42:43], v[8:9], off offset:512
	s_nop 0
	s_waitcnt vmcnt(11)
	v_pk_mul_f32 v[0:1], v[176:177], v[0:1]
	s_nop 0
	v_pk_mul_f32 v[2:3], v[178:179], v[2:3]
	s_nop 0
	s_waitcnt vmcnt(10)
	v_pk_add_f32 v[8:9], v[144:145], 1.0 op_sel_hi:[1,0]
	v_lshl_add_u64 v[12:13], v[22:23], 0, v[40:41]
	s_waitcnt vmcnt(9)
	v_pk_fma_f32 v[0:1], v[8:9], v[0:1], v[160:161]
	v_pk_add_f32 v[8:9], v[146:147], 1.0 op_sel_hi:[1,0]
	v_cvt_pk_bf16_f32 v0, v0, v1
	v_pk_fma_f32 v[2:3], v[8:9], v[2:3], v[162:163]
	v_lshl_add_u64 v[8:9], v[44:45], 0, v[40:41]
	v_cvt_pk_bf16_f32 v1, v2, v3
	global_store_dwordx2 v[42:43], v[0:1], off offset:1024
	s_nop 0
	s_waitcnt vmcnt(9)
	v_pk_mul_f32 v[0:1], v[180:181], v[4:5]
	s_nop 0
	s_waitcnt vmcnt(8)
	v_pk_add_f32 v[4:5], v[148:149], 1.0 op_sel_hi:[1,0]
	s_nop 0
	s_waitcnt vmcnt(7)
	v_pk_fma_f32 v[0:1], v[4:5], v[0:1], v[164:165]
	v_pk_mul_f32 v[4:5], v[6:7], v[20:21] op_sel_hi:[1,0]
	v_cvt_pk_bf16_f32 v0, v0, v1
	v_pk_mul_f32 v[2:3], v[182:183], v[4:5]
	v_pk_add_f32 v[4:5], v[150:151], 1.0 op_sel_hi:[1,0]
	s_nop 0
	v_pk_fma_f32 v[2:3], v[4:5], v[2:3], v[166:167]
	s_nop 0
	v_cvt_pk_bf16_f32 v1, v2, v3
	global_store_dwordx2 v[42:43], v[0:1], off offset:1536
	s_andn2_b64 exec, exec, s[44:45]
	s_cbranch_execnz .LBB0_71
